# speedup vs baseline: 1.0040x; 1.0040x over previous
; __device__ __forceinline__ unsigned cvt_pk_bf16(float lo, float hi) { unsigned r; asm volatile("v_cvt_pk_bf16_f32 %0, %1, %2" : "=v"(r) : "v"(lo), "v"(hi)); return r; }
; __device__ __forceinline__ float bflo(unsigned w) { return __uint_as_float(w << 16); }
; __device__ __forceinline__ float bfhi(unsigned w) { return __uint_as_float(w & 0xffff0000u); }
;     __device__ __forceinline__ void operator()(const f32x4 (&acc)[2][2][4][2], const Unit& u, int wr, int wc, int fr, int fq) const {
;         const int grow = rowoff + u.pm * 256; const bool lat = grow < MLAT; const int cond = lat ? (grow >> 13) : 8;
;         const float* bf = lat ? base_l + (size_t)grow * DM : base_c + (size_t)(grow - MLAT) * DM;
;         bf16_t* hp = hb + (size_t)grow * DM;
;         const int col0 = u.pn * 256 + wc * 32 + 8 * fq; const float* g = gate + cond * 6144 + col0;
;         f32x4 gv[2][2];
; #pragma unroll
;         for (int bj = 0; bj < 2; ++bj)
; #pragma unroll
;             for (int n = 0; n < 2; ++n) gv[bj][n] = *(const f32x4*)(g + bj * 128 + n * 4);
; #pragma unroll
;         for (int ai = 0; ai < 2; ++ai)
; #pragma unroll
;             for (int m = 0; m < 4; ++m) { const size_t off = (size_t)(wr * 64 + fr + ai * 128 + m * 16) * DM + col0;
; #pragma unroll
;                 for (int bj = 0; bj < 2; ++bj) { f32x4 b0, b1;
;                     if (BASE_F32) { b0 = *(const f32x4*)(bf + off + bj * 128); b1 = *(const f32x4*)(bf + off + bj * 128 + 4); }
;                     else { const u32x4 w = *(const u32x4*)(hp + off + bj * 128); b0 = (f32x4){bflo(w.x), bfhi(w.x), bflo(w.y), bfhi(w.y)}; b1 = (f32x4){bflo(w.z), bfhi(w.z), bflo(w.w), bfhi(w.w)}; }
;                     const f32x4 o0 = b0 + gv[bj][0] * acc[ai][bj][m][0], o1 = b1 + gv[bj][1] * acc[ai][bj][m][1]; u32x4 wo;
;                     wo.x = cvt_pk_bf16(o0[0], o0[1]); wo.y = cvt_pk_bf16(o0[2], o0[3]); wo.z = cvt_pk_bf16(o1[0], o1[1]); wo.w = cvt_pk_bf16(o1[2], o1[3]);
;                     *(u32x4*)(hp + off + bj * 128) = wo; } }
.LBB0_532:
	s_lshl_b32 s2, s81, 8
	s_add_i32 s2, s2, s43
	s_min_i32 s3, s2, 0x10000
	s_ashr_i32 s12, s3, 13
	s_mulk_i32 s12, 0x1800
	s_ashr_i32 s3, s2, 31
	s_ashr_i32 s13, s12, 31
	s_lshl_b64 s[2:3], s[2:3], 11
	s_lshl_b64 s[12:13], s[12:13], 2
	s_add_u32 s12, s57, s12
	s_addc_u32 s13, s59, s13
	v_lshl_or_b32 v122, s82, 8, v180
	s_add_u32 s2, s68, s2
	v_ashrrev_i32_e32 v123, 31, v122
	s_addc_u32 s3, s69, s3
	v_lshl_add_u64 v[174:175], v[122:123], 1, s[2:3]
	v_lshl_add_u64 v[186:187], v[174:175], 0, v[154:155]
	global_load_dwordx4 v[182:185], v[186:187], off
	v_lshl_add_u64 v[126:127], v[122:123], 2, s[12:13]
	global_load_dwordx4 v[142:145], v[126:127], off
	global_load_dwordx4 v[134:137], v[126:127], off offset:16
	global_load_dwordx4 v[122:125], v[126:127], off offset:528
	s_nop 0
	global_load_dwordx4 v[126:129], v[126:127], off offset:512
	s_and_b64 vcc, exec, s[38:39]
	s_mov_b64 s[2:3], -1
	v_lshl_add_u64 v[252:253], v[174:175], 0, v[154:155]
	global_load_dwordx4 v[212:215], v[252:253], off offset:256
	v_lshl_add_u64 v[252:253], v[174:175], 0, v[156:157]
	global_load_dwordx4 v[216:219], v[252:253], off
	v_lshl_add_u64 v[252:253], v[174:175], 0, v[156:157]
	global_load_dwordx4 v[220:223], v[252:253], off offset:256
	v_lshl_add_u64 v[252:253], v[174:175], 0, v[158:159]
	global_load_dwordx4 v[224:227], v[252:253], off
	v_lshl_add_u64 v[252:253], v[174:175], 0, v[158:159]
	global_load_dwordx4 v[228:231], v[252:253], off offset:256
	v_lshl_add_u64 v[252:253], v[174:175], 0, v[160:161]
	global_load_dwordx4 v[232:235], v[252:253], off
	v_lshl_add_u64 v[252:253], v[174:175], 0, v[160:161]
	global_load_dwordx4 v[236:239], v[252:253], off offset:256
	v_lshl_add_u64 v[252:253], v[174:175], 0, v[162:163]
	global_load_dwordx4 v[240:243], v[252:253], off
	v_lshl_add_u64 v[252:253], v[174:175], 0, v[162:163]
	global_load_dwordx4 v[244:247], v[252:253], off offset:256
	v_lshl_add_u64 v[252:253], v[174:175], 0, v[164:165]
	global_load_dwordx4 v[248:251], v[252:253], off
	s_waitcnt vmcnt(10)
	v_lshlrev_b32_e32 v188, 16, v182
	v_and_b32_e32 v189, 0xffff0000, v182
	v_lshlrev_b32_e32 v182, 16, v183
	v_and_b32_e32 v183, 0xffff0000, v183
	v_lshlrev_b32_e32 v190, 16, v184
	v_and_b32_e32 v191, 0xffff0000, v184
	v_lshlrev_b32_e32 v184, 16, v185
	v_and_b32_e32 v185, 0xffff0000, v185
	v_pk_fma_f32 v[140:141], v[140:141], v[144:145], v[182:183]
	v_pk_fma_f32 v[138:139], v[138:139], v[142:143], v[188:189]
	v_pk_fma_f32 v[182:183], v[132:133], v[136:137], v[184:185]
	v_pk_fma_f32 v[132:133], v[130:131], v[134:135], v[190:191]
	v_cvt_pk_bf16_f32 v130, v138, v139
	v_cvt_pk_bf16_f32 v131, v140, v141
	s_nop 0
	v_cvt_pk_bf16_f32 v132, v132, v133
	v_cvt_pk_bf16_f32 v133, v182, v183
	v_lshl_add_u64 v[182:183], v[174:175], 0, v[156:157]
	global_store_dwordx4 v[186:187], v[130:133], off
	s_waitcnt vmcnt(10)
	s_nop 0
	v_lshlrev_b32_e32 v130, 16, v212
	v_and_b32_e32 v131, 0xffff0000, v212
	v_lshlrev_b32_e32 v132, 16, v213
	v_and_b32_e32 v133, 0xffff0000, v213
	v_lshlrev_b32_e32 v138, 16, v214
	v_and_b32_e32 v139, 0xffff0000, v214
	v_lshlrev_b32_e32 v140, 16, v215
	v_and_b32_e32 v141, 0xffff0000, v215
	v_pk_fma_f32 v[116:117], v[116:117], v[128:129], v[132:133]
	v_pk_fma_f32 v[114:115], v[114:115], v[126:127], v[130:131]
	v_pk_fma_f32 v[130:131], v[112:113], v[124:125], v[140:141]
	v_pk_fma_f32 v[112:113], v[110:111], v[122:123], v[138:139]
	v_cvt_pk_bf16_f32 v110, v114, v115
	v_cvt_pk_bf16_f32 v111, v116, v117
	s_nop 0
	v_cvt_pk_bf16_f32 v112, v112, v113
	v_cvt_pk_bf16_f32 v113, v130, v131
	v_lshl_add_u64 v[252:253], v[174:175], 0, v[164:165]
	global_load_dwordx4 v[212:215], v[252:253], off offset:256
	s_nop 0
	global_store_dwordx4 v[186:187], v[110:113], off offset:256
	s_waitcnt vmcnt(11)
	s_nop 0
	v_lshlrev_b32_e32 v110, 16, v216
	v_and_b32_e32 v111, 0xffff0000, v216
	v_lshlrev_b32_e32 v112, 16, v217
	v_and_b32_e32 v113, 0xffff0000, v217
	v_lshlrev_b32_e32 v114, 16, v218
	v_and_b32_e32 v115, 0xffff0000, v218
	v_lshlrev_b32_e32 v116, 16, v219
	v_and_b32_e32 v117, 0xffff0000, v219
	v_pk_fma_f32 v[112:113], v[120:121], v[144:145], v[112:113]
	v_pk_fma_f32 v[110:111], v[118:119], v[142:143], v[110:111]
	v_pk_fma_f32 v[116:117], v[108:109], v[136:137], v[116:117]
	v_pk_fma_f32 v[108:109], v[106:107], v[134:135], v[114:115]
	v_cvt_pk_bf16_f32 v106, v110, v111
	v_cvt_pk_bf16_f32 v107, v112, v113
	v_lshl_add_u64 v[114:115], v[174:175], 0, v[158:159]
	v_cvt_pk_bf16_f32 v108, v108, v109
	v_cvt_pk_bf16_f32 v109, v116, v117
	v_lshl_add_u64 v[252:253], v[174:175], 0, v[166:167]
	global_load_dwordx4 v[216:219], v[252:253], off
	s_nop 0
	global_store_dwordx4 v[182:183], v[106:109], off
	s_waitcnt vmcnt(12)
	s_nop 0
	v_lshlrev_b32_e32 v106, 16, v220
	v_and_b32_e32 v107, 0xffff0000, v220
	v_lshlrev_b32_e32 v108, 16, v221
	v_and_b32_e32 v109, 0xffff0000, v221
	v_lshlrev_b32_e32 v110, 16, v222
	v_and_b32_e32 v111, 0xffff0000, v222
	v_lshlrev_b32_e32 v112, 16, v223
	v_and_b32_e32 v113, 0xffff0000, v223
	v_pk_fma_f32 v[100:101], v[100:101], v[128:129], v[108:109]
	v_pk_fma_f32 v[98:99], v[98:99], v[126:127], v[106:107]
	v_pk_fma_f32 v[106:107], v[96:97], v[124:125], v[112:113]
	v_pk_fma_f32 v[96:97], v[94:95], v[122:123], v[110:111]
	v_cvt_pk_bf16_f32 v94, v98, v99
	v_cvt_pk_bf16_f32 v95, v100, v101
	s_nop 0
	v_cvt_pk_bf16_f32 v96, v96, v97
	v_cvt_pk_bf16_f32 v97, v106, v107
	v_lshl_add_u64 v[252:253], v[174:175], 0, v[166:167]
	global_load_dwordx4 v[220:223], v[252:253], off offset:256
	s_nop 0
	global_store_dwordx4 v[182:183], v[94:97], off offset:256
	s_waitcnt vmcnt(13)
; __device__ __forceinline__ unsigned cvt_pk_bf16(float lo, float hi) { unsigned r; asm volatile("v_cvt_pk_bf16_f32 %0, %1, %2" : "=v"(r) : "v"(lo), "v"(hi)); return r; }
; __device__ __forceinline__ float bflo(unsigned w) { return __uint_as_float(w << 16); }
; __device__ __forceinline__ float bfhi(unsigned w) { return __uint_as_float(w & 0xffff0000u); }
;     __device__ __forceinline__ void operator()(const f32x4 (&acc)[2][2][4][2], const Unit& u, int wr, int wc, int fr, int fq) const {
;     ...
;         for (int ai = 0; ai < 2; ++ai)
; #pragma unroll
;             for (int m = 0; m < 4; ++m) { const size_t off = (size_t)(wr * 64 + fr + ai * 128 + m * 16) * DM + col0;
; #pragma unroll
;                 for (int bj = 0; bj < 2; ++bj) { f32x4 b0, b1;
;                     if (BASE_F32) { b0 = *(const f32x4*)(bf + off + bj * 128); b1 = *(const f32x4*)(bf + off + bj * 128 + 4); }
;                     else { const u32x4 w = *(const u32x4*)(hp + off + bj * 128); b0 = (f32x4){bflo(w.x), bfhi(w.x), bflo(w.y), bfhi(w.y)}; b1 = (f32x4){bflo(w.z), bfhi(w.z), bflo(w.w), bfhi(w.w)}; }
;                     const f32x4 o0 = b0 + gv[bj][0] * acc[ai][bj][m][0], o1 = b1 + gv[bj][1] * acc[ai][bj][m][1]; u32x4 wo;
;                     wo.x = cvt_pk_bf16(o0[0], o0[1]); wo.y = cvt_pk_bf16(o0[2], o0[3]); wo.z = cvt_pk_bf16(o1[0], o1[1]); wo.w = cvt_pk_bf16(o1[2], o1[3]);
;                     *(u32x4*)(hp + off + bj * 128) = wo; } }
	s_nop 0
	v_lshlrev_b32_e32 v94, 16, v224
	v_and_b32_e32 v95, 0xffff0000, v224
	v_lshlrev_b32_e32 v96, 16, v225
	v_and_b32_e32 v97, 0xffff0000, v225
	v_lshlrev_b32_e32 v98, 16, v226
	v_and_b32_e32 v99, 0xffff0000, v226
	v_lshlrev_b32_e32 v100, 16, v227
	v_and_b32_e32 v101, 0xffff0000, v227
	v_pk_fma_f32 v[96:97], v[104:105], v[144:145], v[96:97]
	v_pk_fma_f32 v[94:95], v[102:103], v[142:143], v[94:95]
	v_pk_fma_f32 v[100:101], v[92:93], v[136:137], v[100:101]
	v_pk_fma_f32 v[92:93], v[90:91], v[134:135], v[98:99]
	v_cvt_pk_bf16_f32 v90, v94, v95
	v_cvt_pk_bf16_f32 v91, v96, v97
	v_lshl_add_u64 v[98:99], v[174:175], 0, v[160:161]
	v_cvt_pk_bf16_f32 v92, v92, v93
	v_cvt_pk_bf16_f32 v93, v100, v101
	v_lshl_add_u64 v[252:253], v[174:175], 0, v[168:169]
	global_load_dwordx4 v[224:227], v[252:253], off
	s_nop 0
	global_store_dwordx4 v[114:115], v[90:93], off
	s_waitcnt vmcnt(14)
	s_nop 0
	v_lshlrev_b32_e32 v90, 16, v228
	v_and_b32_e32 v91, 0xffff0000, v228
	v_lshlrev_b32_e32 v92, 16, v229
	v_and_b32_e32 v93, 0xffff0000, v229
	v_lshlrev_b32_e32 v94, 16, v230
	v_and_b32_e32 v95, 0xffff0000, v230
	v_lshlrev_b32_e32 v96, 16, v231
	v_and_b32_e32 v97, 0xffff0000, v231
	v_pk_fma_f32 v[84:85], v[84:85], v[128:129], v[92:93]
	v_pk_fma_f32 v[82:83], v[82:83], v[126:127], v[90:91]
	v_pk_fma_f32 v[90:91], v[80:81], v[124:125], v[96:97]
	v_pk_fma_f32 v[80:81], v[78:79], v[122:123], v[94:95]
	v_cvt_pk_bf16_f32 v78, v82, v83
	v_cvt_pk_bf16_f32 v79, v84, v85
	s_nop 0
	v_cvt_pk_bf16_f32 v80, v80, v81
	v_cvt_pk_bf16_f32 v81, v90, v91
	v_lshl_add_u64 v[252:253], v[174:175], 0, v[168:169]
	global_load_dwordx4 v[228:231], v[252:253], off offset:256
	s_nop 0
	global_store_dwordx4 v[114:115], v[78:81], off offset:256
	s_waitcnt vmcnt(15)
	s_nop 0
	v_lshlrev_b32_e32 v78, 16, v232
	v_and_b32_e32 v79, 0xffff0000, v232
	v_lshlrev_b32_e32 v80, 16, v233
	v_and_b32_e32 v81, 0xffff0000, v233
	v_lshlrev_b32_e32 v82, 16, v234
	v_and_b32_e32 v83, 0xffff0000, v234
	v_lshlrev_b32_e32 v84, 16, v235
	v_and_b32_e32 v85, 0xffff0000, v235
	v_pk_fma_f32 v[80:81], v[88:89], v[144:145], v[80:81]
	v_pk_fma_f32 v[78:79], v[86:87], v[142:143], v[78:79]
	v_pk_fma_f32 v[84:85], v[76:77], v[136:137], v[84:85]
	v_pk_fma_f32 v[76:77], v[74:75], v[134:135], v[82:83]
	v_cvt_pk_bf16_f32 v74, v78, v79
	v_cvt_pk_bf16_f32 v75, v80, v81
	v_lshl_add_u64 v[82:83], v[174:175], 0, v[162:163]
	v_cvt_pk_bf16_f32 v76, v76, v77
	v_cvt_pk_bf16_f32 v77, v84, v85
	s_nop 0
	global_store_dwordx4 v[98:99], v[74:77], off
	s_waitcnt vmcnt(15)
	s_nop 0
	v_lshlrev_b32_e32 v74, 16, v236
	v_and_b32_e32 v75, 0xffff0000, v236
	v_lshlrev_b32_e32 v76, 16, v237
	v_and_b32_e32 v77, 0xffff0000, v237
	v_lshlrev_b32_e32 v78, 16, v238
	v_and_b32_e32 v79, 0xffff0000, v238
	v_lshlrev_b32_e32 v80, 16, v239
	v_and_b32_e32 v81, 0xffff0000, v239
	v_pk_fma_f32 v[72:73], v[72:73], v[128:129], v[76:77]
	v_pk_fma_f32 v[70:71], v[70:71], v[126:127], v[74:75]
	v_pk_fma_f32 v[74:75], v[68:69], v[124:125], v[80:81]
	v_pk_fma_f32 v[68:69], v[66:67], v[122:123], v[78:79]
	v_cvt_pk_bf16_f32 v66, v70, v71
	v_cvt_pk_bf16_f32 v67, v72, v73
	s_nop 0
	v_cvt_pk_bf16_f32 v68, v68, v69
	v_cvt_pk_bf16_f32 v69, v74, v75
	s_nop 0
	global_store_dwordx4 v[98:99], v[66:69], off offset:256
	s_waitcnt vmcnt(15)
	s_nop 0
	v_lshlrev_b32_e32 v66, 16, v240
	v_and_b32_e32 v67, 0xffff0000, v240
	v_lshlrev_b32_e32 v68, 16, v241
	v_and_b32_e32 v69, 0xffff0000, v241
	v_lshlrev_b32_e32 v70, 16, v242
	v_and_b32_e32 v71, 0xffff0000, v242
	v_lshlrev_b32_e32 v72, 16, v243
	v_and_b32_e32 v73, 0xffff0000, v243
	v_pk_fma_f32 v[64:65], v[64:65], v[144:145], v[68:69]
	v_pk_fma_f32 v[62:63], v[62:63], v[142:143], v[66:67]
	v_pk_fma_f32 v[66:67], v[60:61], v[136:137], v[72:73]
	v_pk_fma_f32 v[60:61], v[58:59], v[134:135], v[70:71]
	v_cvt_pk_bf16_f32 v58, v62, v63
	v_cvt_pk_bf16_f32 v59, v64, v65
	s_nop 0
	v_cvt_pk_bf16_f32 v60, v60, v61
	v_cvt_pk_bf16_f32 v61, v66, v67
	v_lshl_add_u64 v[66:67], v[174:175], 0, v[164:165]
	global_store_dwordx4 v[82:83], v[58:61], off
	s_waitcnt vmcnt(15)
	s_nop 0
	v_lshlrev_b32_e32 v58, 16, v244
	v_and_b32_e32 v59, 0xffff0000, v244
	v_lshlrev_b32_e32 v60, 16, v245
	v_and_b32_e32 v61, 0xffff0000, v245
	v_lshlrev_b32_e32 v62, 16, v246
	v_and_b32_e32 v63, 0xffff0000, v246
	v_lshlrev_b32_e32 v64, 16, v247
	v_and_b32_e32 v65, 0xffff0000, v247
	v_pk_fma_f32 v[52:53], v[52:53], v[128:129], v[60:61]
	v_pk_fma_f32 v[50:51], v[50:51], v[126:127], v[58:59]
	v_pk_fma_f32 v[58:59], v[48:49], v[124:125], v[64:65]
	v_pk_fma_f32 v[48:49], v[46:47], v[122:123], v[62:63]
	v_cvt_pk_bf16_f32 v46, v50, v51
	v_cvt_pk_bf16_f32 v47, v52, v53
	s_nop 0
	v_cvt_pk_bf16_f32 v48, v48, v49
	v_cvt_pk_bf16_f32 v49, v58, v59
	s_nop 0
	global_store_dwordx4 v[82:83], v[46:49], off offset:256
	s_waitcnt vmcnt(15)
; __device__ __forceinline__ unsigned cvt_pk_bf16(float lo, float hi) { unsigned r; asm volatile("v_cvt_pk_bf16_f32 %0, %1, %2" : "=v"(r) : "v"(lo), "v"(hi)); return r; }
; #define PG8_BAR __builtin_amdgcn_s_barrier()
; __device__ __forceinline__ float bflo(unsigned w) { return __uint_as_float(w << 16); }
; __device__ __forceinline__ float bfhi(unsigned w) { return __uint_as_float(w & 0xffff0000u); }
; template <class Epi, class Sched, bool ALIGN_EPI = false, bool SP2 = false>
; __device__ __forceinline__ void gemm_phase(PG8_LAS unsigned char* lds, const Gemm g, const Sched& S, const Epi& E) {
;     ...
;         if constexpr (ALIGN_EPI) { if (wr == 0) PG8_BAR; }
;         if constexpr (!Epi::AFTER_DRAIN) { E(acc, cur, wr, wc, fr, fq); S.done(cur); }
;         if (!has_next) break;
; #pragma unroll
;         for (int a = 0; a < 2; ++a)
; #pragma unroll
;             for (int b = 0; b < 2; ++b)
; #pragma unroll
;                 for (int m = 0; m < 4; ++m)
; #pragma unroll
;                     for (int n = 0; n < 2; ++n) acc[a][b][m][n] = (f32x4){0.f, 0.f, 0.f, 0.f};
;         cur = nxt; cA = nA; cB = nB; ++ui;
;         if constexpr (ALIGN_EPI) { if (wr == 1) PG8_BAR; }
;     }
;     __device__ __forceinline__ void operator()(const f32x4 (&acc)[2][2][4][2], const Unit& u, int wr, int wc, int fr, int fq) const {
;     ...
;         for (int ai = 0; ai < 2; ++ai)
; #pragma unroll
;             for (int m = 0; m < 4; ++m) { const size_t off = (size_t)(wr * 64 + fr + ai * 128 + m * 16) * DM + col0;
; #pragma unroll
;                 for (int bj = 0; bj < 2; ++bj) { f32x4 b0, b1;
;                     if (BASE_F32) { b0 = *(const f32x4*)(bf + off + bj * 128); b1 = *(const f32x4*)(bf + off + bj * 128 + 4); }
;                     else { const u32x4 w = *(const u32x4*)(hp + off + bj * 128); b0 = (f32x4){bflo(w.x), bfhi(w.x), bflo(w.y), bfhi(w.y)}; b1 = (f32x4){bflo(w.z), bfhi(w.z), bflo(w.w), bfhi(w.w)}; }
;                     const f32x4 o0 = b0 + gv[bj][0] * acc[ai][bj][m][0], o1 = b1 + gv[bj][1] * acc[ai][bj][m][1]; u32x4 wo;
;                     wo.x = cvt_pk_bf16(o0[0], o0[1]); wo.y = cvt_pk_bf16(o0[2], o0[3]); wo.z = cvt_pk_bf16(o1[0], o1[1]); wo.w = cvt_pk_bf16(o1[2], o1[3]);
;                     *(u32x4*)(hp + off + bj * 128) = wo; } }
	s_nop 0
	v_lshlrev_b32_e32 v46, 16, v248
	v_and_b32_e32 v47, 0xffff0000, v248
	v_lshlrev_b32_e32 v48, 16, v249
	v_and_b32_e32 v49, 0xffff0000, v249
	v_lshlrev_b32_e32 v50, 16, v250
	v_and_b32_e32 v51, 0xffff0000, v250
	v_lshlrev_b32_e32 v52, 16, v251
	v_and_b32_e32 v53, 0xffff0000, v251
	v_pk_fma_f32 v[48:49], v[56:57], v[144:145], v[48:49]
	v_pk_fma_f32 v[46:47], v[54:55], v[142:143], v[46:47]
	v_pk_fma_f32 v[52:53], v[44:45], v[136:137], v[52:53]
	v_pk_fma_f32 v[44:45], v[42:43], v[134:135], v[50:51]
	v_cvt_pk_bf16_f32 v42, v46, v47
	v_cvt_pk_bf16_f32 v43, v48, v49
	v_lshl_add_u64 v[50:51], v[174:175], 0, v[166:167]
	v_cvt_pk_bf16_f32 v44, v44, v45
	v_cvt_pk_bf16_f32 v45, v52, v53
	s_nop 0
	global_store_dwordx4 v[66:67], v[42:45], off
	s_waitcnt vmcnt(14)
	s_nop 0
	v_lshlrev_b32_e32 v42, 16, v212
	v_and_b32_e32 v43, 0xffff0000, v212
	v_lshlrev_b32_e32 v44, 16, v213
	v_and_b32_e32 v45, 0xffff0000, v213
	v_lshlrev_b32_e32 v46, 16, v214
	v_and_b32_e32 v47, 0xffff0000, v214
	v_lshlrev_b32_e32 v48, 16, v215
	v_and_b32_e32 v49, 0xffff0000, v215
	v_pk_fma_f32 v[36:37], v[36:37], v[128:129], v[44:45]
	v_pk_fma_f32 v[34:35], v[34:35], v[126:127], v[42:43]
	v_pk_fma_f32 v[42:43], v[32:33], v[124:125], v[48:49]
	v_pk_fma_f32 v[32:33], v[30:31], v[122:123], v[46:47]
	v_cvt_pk_bf16_f32 v30, v34, v35
	v_cvt_pk_bf16_f32 v31, v36, v37
	s_nop 0
	v_cvt_pk_bf16_f32 v32, v32, v33
	v_cvt_pk_bf16_f32 v33, v42, v43
	s_nop 0
	global_store_dwordx4 v[66:67], v[30:33], off offset:256
	s_waitcnt vmcnt(13)
	s_nop 0
	v_lshlrev_b32_e32 v30, 16, v216
	v_and_b32_e32 v31, 0xffff0000, v216
	v_lshlrev_b32_e32 v32, 16, v217
	v_and_b32_e32 v33, 0xffff0000, v217
	v_lshlrev_b32_e32 v34, 16, v218
	v_and_b32_e32 v35, 0xffff0000, v218
	v_lshlrev_b32_e32 v36, 16, v219
	v_and_b32_e32 v37, 0xffff0000, v219
	v_pk_fma_f32 v[32:33], v[40:41], v[144:145], v[32:33]
	v_pk_fma_f32 v[30:31], v[38:39], v[142:143], v[30:31]
	v_pk_fma_f32 v[36:37], v[28:29], v[136:137], v[36:37]
	v_pk_fma_f32 v[28:29], v[26:27], v[134:135], v[34:35]
	v_cvt_pk_bf16_f32 v26, v30, v31
	v_cvt_pk_bf16_f32 v27, v32, v33
	v_lshl_add_u64 v[34:35], v[174:175], 0, v[168:169]
	v_cvt_pk_bf16_f32 v28, v28, v29
	v_cvt_pk_bf16_f32 v29, v36, v37
	s_nop 0
	global_store_dwordx4 v[50:51], v[26:29], off
	s_waitcnt vmcnt(12)
	s_nop 0
	v_lshlrev_b32_e32 v26, 16, v220
	v_and_b32_e32 v27, 0xffff0000, v220
	v_lshlrev_b32_e32 v28, 16, v221
	v_and_b32_e32 v29, 0xffff0000, v221
	v_lshlrev_b32_e32 v30, 16, v222
	v_and_b32_e32 v31, 0xffff0000, v222
	v_lshlrev_b32_e32 v32, 16, v223
	v_and_b32_e32 v33, 0xffff0000, v223
	v_pk_fma_f32 v[20:21], v[20:21], v[128:129], v[28:29]
	v_pk_fma_f32 v[18:19], v[18:19], v[126:127], v[26:27]
	v_pk_fma_f32 v[26:27], v[16:17], v[124:125], v[32:33]
	v_pk_fma_f32 v[16:17], v[14:15], v[122:123], v[30:31]
	v_cvt_pk_bf16_f32 v14, v18, v19
	v_cvt_pk_bf16_f32 v15, v20, v21
	s_nop 0
	v_cvt_pk_bf16_f32 v16, v16, v17
	v_cvt_pk_bf16_f32 v17, v26, v27
	s_nop 0
	global_store_dwordx4 v[50:51], v[14:17], off offset:256
	s_waitcnt vmcnt(11)
	s_nop 0
	v_lshlrev_b32_e32 v14, 16, v224
	v_and_b32_e32 v15, 0xffff0000, v224
	v_lshlrev_b32_e32 v16, 16, v225
	v_and_b32_e32 v17, 0xffff0000, v225
	v_lshlrev_b32_e32 v18, 16, v226
	v_and_b32_e32 v19, 0xffff0000, v226
	v_lshlrev_b32_e32 v20, 16, v227
	v_and_b32_e32 v21, 0xffff0000, v227
	v_pk_fma_f32 v[16:17], v[24:25], v[144:145], v[16:17]
	v_pk_fma_f32 v[14:15], v[22:23], v[142:143], v[14:15]
	v_pk_fma_f32 v[20:21], v[12:13], v[136:137], v[20:21]
	v_pk_fma_f32 v[12:13], v[10:11], v[134:135], v[18:19]
	v_cvt_pk_bf16_f32 v10, v14, v15
	v_cvt_pk_bf16_f32 v11, v16, v17
	s_nop 0
	v_cvt_pk_bf16_f32 v12, v12, v13
	v_cvt_pk_bf16_f32 v13, v20, v21
	s_nop 0
	global_store_dwordx4 v[34:35], v[10:13], off
	s_waitcnt vmcnt(10)
	s_nop 0
	v_lshlrev_b32_e32 v10, 16, v228
	v_and_b32_e32 v11, 0xffff0000, v228
	v_lshlrev_b32_e32 v12, 16, v229
	v_and_b32_e32 v13, 0xffff0000, v229
	v_lshlrev_b32_e32 v14, 16, v230
	v_and_b32_e32 v15, 0xffff0000, v230
	v_lshlrev_b32_e32 v16, 16, v231
	v_and_b32_e32 v17, 0xffff0000, v231
	v_pk_fma_f32 v[6:7], v[6:7], v[126:127], v[10:11]
	v_pk_fma_f32 v[10:11], v[4:5], v[124:125], v[16:17]
	v_pk_fma_f32 v[4:5], v[2:3], v[122:123], v[14:15]
	v_pk_fma_f32 v[8:9], v[8:9], v[128:129], v[12:13]
	v_cvt_pk_bf16_f32 v2, v6, v7
	s_nop 0
	v_cvt_pk_bf16_f32 v3, v8, v9
	v_cvt_pk_bf16_f32 v4, v4, v5
	v_cvt_pk_bf16_f32 v5, v10, v11
	global_store_dwordx4 v[34:35], v[2:5], off offset:256
	s_cbranch_vccnz .LBB0_521
	s_andn2_b64 vcc, exec, s[60:61]
	s_cbranch_vccnz .LBB0_520
	s_barrier
	s_branch .LBB0_520

; __device__ __forceinline__ unsigned cvt_pk_bf16(float lo, float hi) { unsigned r; asm volatile("v_cvt_pk_bf16_f32 %0, %1, %2" : "=v"(r) : "v"(lo), "v"(hi)); return r; }
; __device__ __forceinline__ float bflo(unsigned w) { return __uint_as_float(w << 16); }
; __device__ __forceinline__ float bfhi(unsigned w) { return __uint_as_float(w & 0xffff0000u); }
;     __device__ __forceinline__ void operator()(const f32x4 (&acc)[2][2][4][2], const Unit& u, int wr, int wc, int fr, int fq) const {
;         const int grow = rowoff + u.pm * 256; const bool lat = grow < MLAT; const int cond = lat ? (grow >> 13) : 8;
;         const float* bf = lat ? base_l + (size_t)grow * DM : base_c + (size_t)(grow - MLAT) * DM;
;         bf16_t* hp = hb + (size_t)grow * DM;
;         const int col0 = u.pn * 256 + wc * 32 + 8 * fq; const float* g = gate + cond * 6144 + col0;
;         f32x4 gv[2][2];
; #pragma unroll
;         for (int bj = 0; bj < 2; ++bj)
; #pragma unroll
;             for (int n = 0; n < 2; ++n) gv[bj][n] = *(const f32x4*)(g + bj * 128 + n * 4);
; #pragma unroll
;         for (int ai = 0; ai < 2; ++ai)
; #pragma unroll
;             for (int m = 0; m < 4; ++m) { const size_t off = (size_t)(wr * 64 + fr + ai * 128 + m * 16) * DM + col0;
; #pragma unroll
;                 for (int bj = 0; bj < 2; ++bj) { f32x4 b0, b1;
;                     if (BASE_F32) { b0 = *(const f32x4*)(bf + off + bj * 128); b1 = *(const f32x4*)(bf + off + bj * 128 + 4); }
;                     else { const u32x4 w = *(const u32x4*)(hp + off + bj * 128); b0 = (f32x4){bflo(w.x), bfhi(w.x), bflo(w.y), bfhi(w.y)}; b1 = (f32x4){bflo(w.z), bfhi(w.z), bflo(w.w), bfhi(w.w)}; }
;                     const f32x4 o0 = b0 + gv[bj][0] * acc[ai][bj][m][0], o1 = b1 + gv[bj][1] * acc[ai][bj][m][1]; u32x4 wo;
;                     wo.x = cvt_pk_bf16(o0[0], o0[1]); wo.y = cvt_pk_bf16(o0[2], o0[3]); wo.z = cvt_pk_bf16(o1[0], o1[1]); wo.w = cvt_pk_bf16(o1[2], o1[3]);
;                     *(u32x4*)(hp + off + bj * 128) = wo; } }
.LBB0_929:
	s_lshl_b32 s12, s30, 8
	s_min_i32 s13, s12, 0x10000
	s_ashr_i32 s23, s13, 13
	s_mul_i32 s34, s23, 0x1800
	s_ashr_i32 s13, s12, 31
	s_ashr_i32 s35, s34, 31
	s_lshl_b64 s[12:13], s[12:13], 11
	s_lshl_b64 s[34:35], s[34:35], 2
	s_add_u32 s34, s45, s34
	s_addc_u32 s35, s46, s35
	v_lshl_or_b32 v120, s51, 8, v179
	s_add_u32 s12, s68, s12
	v_ashrrev_i32_e32 v121, 31, v120
	s_addc_u32 s13, s69, s13
	v_lshl_add_u64 v[176:177], v[120:121], 1, s[12:13]
	v_lshl_add_u64 v[188:189], v[176:177], 0, v[152:153]
	global_load_dwordx4 v[184:187], v[188:189], off
	v_lshl_add_u64 v[124:125], v[120:121], 2, s[34:35]
	global_load_dwordx4 v[140:143], v[124:125], off
	global_load_dwordx4 v[132:135], v[124:125], off offset:16
	global_load_dwordx4 v[120:123], v[124:125], off offset:528
	s_nop 0
	global_load_dwordx4 v[124:127], v[124:125], off offset:512
	s_andn2_b64 vcc, exec, s[38:39]
	s_mov_b64 s[12:13], -1
	v_lshl_add_u64 v[252:253], v[176:177], 0, v[152:153]
	global_load_dwordx4 v[212:215], v[252:253], off offset:256
	v_lshl_add_u64 v[252:253], v[176:177], 0, v[154:155]
	global_load_dwordx4 v[216:219], v[252:253], off
	v_lshl_add_u64 v[252:253], v[176:177], 0, v[154:155]
	global_load_dwordx4 v[220:223], v[252:253], off offset:256
	v_lshl_add_u64 v[252:253], v[176:177], 0, v[156:157]
	global_load_dwordx4 v[224:227], v[252:253], off
	v_lshl_add_u64 v[252:253], v[176:177], 0, v[156:157]
	global_load_dwordx4 v[228:231], v[252:253], off offset:256
	v_lshl_add_u64 v[252:253], v[176:177], 0, v[158:159]
	global_load_dwordx4 v[232:235], v[252:253], off
	v_lshl_add_u64 v[252:253], v[176:177], 0, v[158:159]
	global_load_dwordx4 v[236:239], v[252:253], off offset:256
	v_lshl_add_u64 v[252:253], v[176:177], 0, v[160:161]
	global_load_dwordx4 v[240:243], v[252:253], off
	v_lshl_add_u64 v[252:253], v[176:177], 0, v[160:161]
	global_load_dwordx4 v[244:247], v[252:253], off offset:256
	v_lshl_add_u64 v[252:253], v[176:177], 0, v[162:163]
	global_load_dwordx4 v[248:251], v[252:253], off
	s_waitcnt vmcnt(10)
	v_lshlrev_b32_e32 v190, 16, v184
	v_and_b32_e32 v191, 0xffff0000, v184
	v_lshlrev_b32_e32 v184, 16, v185
	v_and_b32_e32 v185, 0xffff0000, v185
	v_lshlrev_b32_e32 v196, 16, v186
	v_and_b32_e32 v197, 0xffff0000, v186
	v_lshlrev_b32_e32 v186, 16, v187
	v_and_b32_e32 v187, 0xffff0000, v187
	v_pk_fma_f32 v[138:139], v[138:139], v[142:143], v[184:185]
	v_pk_fma_f32 v[136:137], v[136:137], v[140:141], v[190:191]
	v_pk_fma_f32 v[184:185], v[130:131], v[134:135], v[186:187]
	v_pk_fma_f32 v[130:131], v[128:129], v[132:133], v[196:197]
	v_cvt_pk_bf16_f32 v128, v136, v137
	v_cvt_pk_bf16_f32 v129, v138, v139
	s_nop 0
	v_cvt_pk_bf16_f32 v130, v130, v131
	v_cvt_pk_bf16_f32 v131, v184, v185
	v_lshl_add_u64 v[184:185], v[176:177], 0, v[154:155]
	global_store_dwordx4 v[188:189], v[128:131], off
	s_waitcnt vmcnt(10)
	s_nop 0
	v_lshlrev_b32_e32 v128, 16, v212
	v_and_b32_e32 v129, 0xffff0000, v212
	v_lshlrev_b32_e32 v130, 16, v213
	v_and_b32_e32 v131, 0xffff0000, v213
	v_lshlrev_b32_e32 v136, 16, v214
	v_and_b32_e32 v137, 0xffff0000, v214
	v_lshlrev_b32_e32 v138, 16, v215
	v_and_b32_e32 v139, 0xffff0000, v215
	v_pk_fma_f32 v[114:115], v[114:115], v[126:127], v[130:131]
	v_pk_fma_f32 v[112:113], v[112:113], v[124:125], v[128:129]
	v_pk_fma_f32 v[128:129], v[110:111], v[122:123], v[138:139]
	v_pk_fma_f32 v[110:111], v[108:109], v[120:121], v[136:137]
	v_cvt_pk_bf16_f32 v108, v112, v113
	v_cvt_pk_bf16_f32 v109, v114, v115
	s_nop 0
	v_cvt_pk_bf16_f32 v110, v110, v111
	v_cvt_pk_bf16_f32 v111, v128, v129
	v_lshl_add_u64 v[252:253], v[176:177], 0, v[162:163]
	global_load_dwordx4 v[212:215], v[252:253], off offset:256
	s_nop 0
	global_store_dwordx4 v[188:189], v[108:111], off offset:256
	s_waitcnt vmcnt(11)
	s_nop 0
	v_lshlrev_b32_e32 v108, 16, v216
	v_and_b32_e32 v109, 0xffff0000, v216
	v_lshlrev_b32_e32 v110, 16, v217
	v_and_b32_e32 v111, 0xffff0000, v217
	v_lshlrev_b32_e32 v112, 16, v218
	v_and_b32_e32 v113, 0xffff0000, v218
	v_lshlrev_b32_e32 v114, 16, v219
	v_and_b32_e32 v115, 0xffff0000, v219
	v_pk_fma_f32 v[110:111], v[118:119], v[142:143], v[110:111]
	v_pk_fma_f32 v[108:109], v[116:117], v[140:141], v[108:109]
	v_pk_fma_f32 v[114:115], v[106:107], v[134:135], v[114:115]
	v_pk_fma_f32 v[106:107], v[104:105], v[132:133], v[112:113]
	v_cvt_pk_bf16_f32 v104, v108, v109
	v_cvt_pk_bf16_f32 v105, v110, v111
	v_lshl_add_u64 v[112:113], v[176:177], 0, v[156:157]
	v_cvt_pk_bf16_f32 v106, v106, v107
	v_cvt_pk_bf16_f32 v107, v114, v115
	v_lshl_add_u64 v[252:253], v[176:177], 0, v[164:165]
	global_load_dwordx4 v[216:219], v[252:253], off
	s_nop 0
	global_store_dwordx4 v[184:185], v[104:107], off
	s_waitcnt vmcnt(12)
	s_nop 0
	v_lshlrev_b32_e32 v104, 16, v220
	v_and_b32_e32 v105, 0xffff0000, v220
	v_lshlrev_b32_e32 v106, 16, v221
	v_and_b32_e32 v107, 0xffff0000, v221
	v_lshlrev_b32_e32 v108, 16, v222
	v_and_b32_e32 v109, 0xffff0000, v222
	v_lshlrev_b32_e32 v110, 16, v223
	v_and_b32_e32 v111, 0xffff0000, v223
	v_pk_fma_f32 v[98:99], v[98:99], v[126:127], v[106:107]
	v_pk_fma_f32 v[96:97], v[96:97], v[124:125], v[104:105]
	v_pk_fma_f32 v[104:105], v[94:95], v[122:123], v[110:111]
	v_pk_fma_f32 v[94:95], v[92:93], v[120:121], v[108:109]
	v_cvt_pk_bf16_f32 v92, v96, v97
	v_cvt_pk_bf16_f32 v93, v98, v99
	s_nop 0
	v_cvt_pk_bf16_f32 v94, v94, v95
	v_cvt_pk_bf16_f32 v95, v104, v105
	v_lshl_add_u64 v[252:253], v[176:177], 0, v[164:165]
	global_load_dwordx4 v[220:223], v[252:253], off offset:256
	s_nop 0
	global_store_dwordx4 v[184:185], v[92:95], off offset:256
	s_waitcnt vmcnt(13)
; __device__ __forceinline__ unsigned cvt_pk_bf16(float lo, float hi) { unsigned r; asm volatile("v_cvt_pk_bf16_f32 %0, %1, %2" : "=v"(r) : "v"(lo), "v"(hi)); return r; }
; __device__ __forceinline__ float bflo(unsigned w) { return __uint_as_float(w << 16); }
; __device__ __forceinline__ float bfhi(unsigned w) { return __uint_as_float(w & 0xffff0000u); }
;     __device__ __forceinline__ void operator()(const f32x4 (&acc)[2][2][4][2], const Unit& u, int wr, int wc, int fr, int fq) const {
;     ...
;         for (int ai = 0; ai < 2; ++ai)
; #pragma unroll
;             for (int m = 0; m < 4; ++m) { const size_t off = (size_t)(wr * 64 + fr + ai * 128 + m * 16) * DM + col0;
; #pragma unroll
;                 for (int bj = 0; bj < 2; ++bj) { f32x4 b0, b1;
;                     if (BASE_F32) { b0 = *(const f32x4*)(bf + off + bj * 128); b1 = *(const f32x4*)(bf + off + bj * 128 + 4); }
;                     else { const u32x4 w = *(const u32x4*)(hp + off + bj * 128); b0 = (f32x4){bflo(w.x), bfhi(w.x), bflo(w.y), bfhi(w.y)}; b1 = (f32x4){bflo(w.z), bfhi(w.z), bflo(w.w), bfhi(w.w)}; }
;                     const f32x4 o0 = b0 + gv[bj][0] * acc[ai][bj][m][0], o1 = b1 + gv[bj][1] * acc[ai][bj][m][1]; u32x4 wo;
;                     wo.x = cvt_pk_bf16(o0[0], o0[1]); wo.y = cvt_pk_bf16(o0[2], o0[3]); wo.z = cvt_pk_bf16(o1[0], o1[1]); wo.w = cvt_pk_bf16(o1[2], o1[3]);
;                     *(u32x4*)(hp + off + bj * 128) = wo; } }
	s_nop 0
	v_lshlrev_b32_e32 v92, 16, v224
	v_and_b32_e32 v93, 0xffff0000, v224
	v_lshlrev_b32_e32 v94, 16, v225
	v_and_b32_e32 v95, 0xffff0000, v225
	v_lshlrev_b32_e32 v96, 16, v226
	v_and_b32_e32 v97, 0xffff0000, v226
	v_lshlrev_b32_e32 v98, 16, v227
	v_and_b32_e32 v99, 0xffff0000, v227
	v_pk_fma_f32 v[94:95], v[102:103], v[142:143], v[94:95]
	v_pk_fma_f32 v[92:93], v[100:101], v[140:141], v[92:93]
	v_pk_fma_f32 v[98:99], v[90:91], v[134:135], v[98:99]
	v_pk_fma_f32 v[90:91], v[88:89], v[132:133], v[96:97]
	v_cvt_pk_bf16_f32 v88, v92, v93
	v_cvt_pk_bf16_f32 v89, v94, v95
	v_lshl_add_u64 v[96:97], v[176:177], 0, v[158:159]
	v_cvt_pk_bf16_f32 v90, v90, v91
	v_cvt_pk_bf16_f32 v91, v98, v99
	v_lshl_add_u64 v[252:253], v[176:177], 0, v[166:167]
	global_load_dwordx4 v[224:227], v[252:253], off
	s_nop 0
	global_store_dwordx4 v[112:113], v[88:91], off
	s_waitcnt vmcnt(14)
	s_nop 0
	v_lshlrev_b32_e32 v88, 16, v228
	v_and_b32_e32 v89, 0xffff0000, v228
	v_lshlrev_b32_e32 v90, 16, v229
	v_and_b32_e32 v91, 0xffff0000, v229
	v_lshlrev_b32_e32 v92, 16, v230
	v_and_b32_e32 v93, 0xffff0000, v230
	v_lshlrev_b32_e32 v94, 16, v231
	v_and_b32_e32 v95, 0xffff0000, v231
	v_pk_fma_f32 v[82:83], v[82:83], v[126:127], v[90:91]
	v_pk_fma_f32 v[80:81], v[80:81], v[124:125], v[88:89]
	v_pk_fma_f32 v[88:89], v[78:79], v[122:123], v[94:95]
	v_pk_fma_f32 v[78:79], v[76:77], v[120:121], v[92:93]
	v_cvt_pk_bf16_f32 v76, v80, v81
	v_cvt_pk_bf16_f32 v77, v82, v83
	s_nop 0
	v_cvt_pk_bf16_f32 v78, v78, v79
	v_cvt_pk_bf16_f32 v79, v88, v89
	v_lshl_add_u64 v[252:253], v[176:177], 0, v[166:167]
	global_load_dwordx4 v[228:231], v[252:253], off offset:256
	s_nop 0
	global_store_dwordx4 v[112:113], v[76:79], off offset:256
	s_waitcnt vmcnt(15)
	s_nop 0
	v_lshlrev_b32_e32 v76, 16, v232
	v_and_b32_e32 v77, 0xffff0000, v232
	v_lshlrev_b32_e32 v78, 16, v233
	v_and_b32_e32 v79, 0xffff0000, v233
	v_lshlrev_b32_e32 v80, 16, v234
	v_and_b32_e32 v81, 0xffff0000, v234
	v_lshlrev_b32_e32 v82, 16, v235
	v_and_b32_e32 v83, 0xffff0000, v235
	v_pk_fma_f32 v[78:79], v[86:87], v[142:143], v[78:79]
	v_pk_fma_f32 v[76:77], v[84:85], v[140:141], v[76:77]
	v_pk_fma_f32 v[82:83], v[74:75], v[134:135], v[82:83]
	v_pk_fma_f32 v[74:75], v[72:73], v[132:133], v[80:81]
	v_cvt_pk_bf16_f32 v72, v76, v77
	v_cvt_pk_bf16_f32 v73, v78, v79
	v_lshl_add_u64 v[80:81], v[176:177], 0, v[160:161]
	v_cvt_pk_bf16_f32 v74, v74, v75
	v_cvt_pk_bf16_f32 v75, v82, v83
	s_nop 0
	global_store_dwordx4 v[96:97], v[72:75], off
	s_waitcnt vmcnt(15)
	s_nop 0
	v_lshlrev_b32_e32 v72, 16, v236
	v_and_b32_e32 v73, 0xffff0000, v236
	v_lshlrev_b32_e32 v74, 16, v237
	v_and_b32_e32 v75, 0xffff0000, v237
	v_lshlrev_b32_e32 v76, 16, v238
	v_and_b32_e32 v77, 0xffff0000, v238
	v_lshlrev_b32_e32 v78, 16, v239
	v_and_b32_e32 v79, 0xffff0000, v239
	v_pk_fma_f32 v[70:71], v[70:71], v[126:127], v[74:75]
	v_pk_fma_f32 v[68:69], v[68:69], v[124:125], v[72:73]
	v_pk_fma_f32 v[72:73], v[66:67], v[122:123], v[78:79]
	v_pk_fma_f32 v[66:67], v[64:65], v[120:121], v[76:77]
	v_cvt_pk_bf16_f32 v64, v68, v69
	v_cvt_pk_bf16_f32 v65, v70, v71
	s_nop 0
	v_cvt_pk_bf16_f32 v66, v66, v67
	v_cvt_pk_bf16_f32 v67, v72, v73
	s_nop 0
	global_store_dwordx4 v[96:97], v[64:67], off offset:256
	s_waitcnt vmcnt(15)
	s_nop 0
	v_lshlrev_b32_e32 v64, 16, v240
	v_and_b32_e32 v65, 0xffff0000, v240
	v_lshlrev_b32_e32 v66, 16, v241
	v_and_b32_e32 v67, 0xffff0000, v241
	v_lshlrev_b32_e32 v68, 16, v242
	v_and_b32_e32 v69, 0xffff0000, v242
	v_lshlrev_b32_e32 v70, 16, v243
	v_and_b32_e32 v71, 0xffff0000, v243
	v_pk_fma_f32 v[62:63], v[62:63], v[142:143], v[66:67]
	v_pk_fma_f32 v[60:61], v[60:61], v[140:141], v[64:65]
	v_pk_fma_f32 v[64:65], v[58:59], v[134:135], v[70:71]
	v_pk_fma_f32 v[58:59], v[56:57], v[132:133], v[68:69]
	v_cvt_pk_bf16_f32 v56, v60, v61
	v_cvt_pk_bf16_f32 v57, v62, v63
	s_nop 0
	v_cvt_pk_bf16_f32 v58, v58, v59
	v_cvt_pk_bf16_f32 v59, v64, v65
	v_lshl_add_u64 v[64:65], v[176:177], 0, v[162:163]
	global_store_dwordx4 v[80:81], v[56:59], off
	s_waitcnt vmcnt(15)
	s_nop 0
	v_lshlrev_b32_e32 v56, 16, v244
	v_and_b32_e32 v57, 0xffff0000, v244
	v_lshlrev_b32_e32 v58, 16, v245
	v_and_b32_e32 v59, 0xffff0000, v245
	v_lshlrev_b32_e32 v60, 16, v246
	v_and_b32_e32 v61, 0xffff0000, v246
	v_lshlrev_b32_e32 v62, 16, v247
	v_and_b32_e32 v63, 0xffff0000, v247
	v_pk_fma_f32 v[50:51], v[50:51], v[126:127], v[58:59]
	v_pk_fma_f32 v[48:49], v[48:49], v[124:125], v[56:57]
	v_pk_fma_f32 v[56:57], v[46:47], v[122:123], v[62:63]
	v_pk_fma_f32 v[46:47], v[44:45], v[120:121], v[60:61]
	v_cvt_pk_bf16_f32 v44, v48, v49
	v_cvt_pk_bf16_f32 v45, v50, v51
	s_nop 0
	v_cvt_pk_bf16_f32 v46, v46, v47
	v_cvt_pk_bf16_f32 v47, v56, v57
	s_nop 0
	global_store_dwordx4 v[80:81], v[44:47], off offset:256
	s_waitcnt vmcnt(15)
; __device__ __forceinline__ unsigned cvt_pk_bf16(float lo, float hi) { unsigned r; asm volatile("v_cvt_pk_bf16_f32 %0, %1, %2" : "=v"(r) : "v"(lo), "v"(hi)); return r; }
; #define PG8_BAR __builtin_amdgcn_s_barrier()
; __device__ __forceinline__ float bflo(unsigned w) { return __uint_as_float(w << 16); }
; __device__ __forceinline__ float bfhi(unsigned w) { return __uint_as_float(w & 0xffff0000u); }
; template <class Epi, class Sched, bool ALIGN_EPI = false, bool SP2 = false>
; __device__ __forceinline__ void gemm_phase(PG8_LAS unsigned char* lds, const Gemm g, const Sched& S, const Epi& E) {
;     ...
;         if constexpr (ALIGN_EPI) { if (wr == 0) PG8_BAR; }
;         if constexpr (!Epi::AFTER_DRAIN) { E(acc, cur, wr, wc, fr, fq); S.done(cur); }
;         if (!has_next) break;
; #pragma unroll
;         for (int a = 0; a < 2; ++a)
; #pragma unroll
;             for (int b = 0; b < 2; ++b)
; #pragma unroll
;                 for (int m = 0; m < 4; ++m)
; #pragma unroll
;                     for (int n = 0; n < 2; ++n) acc[a][b][m][n] = (f32x4){0.f, 0.f, 0.f, 0.f};
;         cur = nxt; cA = nA; cB = nB; ++ui;
;         if constexpr (ALIGN_EPI) { if (wr == 1) PG8_BAR; }
;     }
;     __device__ __forceinline__ void operator()(const f32x4 (&acc)[2][2][4][2], const Unit& u, int wr, int wc, int fr, int fq) const {
;     ...
;         for (int ai = 0; ai < 2; ++ai)
; #pragma unroll
;             for (int m = 0; m < 4; ++m) { const size_t off = (size_t)(wr * 64 + fr + ai * 128 + m * 16) * DM + col0;
; #pragma unroll
;                 for (int bj = 0; bj < 2; ++bj) { f32x4 b0, b1;
;                     if (BASE_F32) { b0 = *(const f32x4*)(bf + off + bj * 128); b1 = *(const f32x4*)(bf + off + bj * 128 + 4); }
;                     else { const u32x4 w = *(const u32x4*)(hp + off + bj * 128); b0 = (f32x4){bflo(w.x), bfhi(w.x), bflo(w.y), bfhi(w.y)}; b1 = (f32x4){bflo(w.z), bfhi(w.z), bflo(w.w), bfhi(w.w)}; }
;                     const f32x4 o0 = b0 + gv[bj][0] * acc[ai][bj][m][0], o1 = b1 + gv[bj][1] * acc[ai][bj][m][1]; u32x4 wo;
;                     wo.x = cvt_pk_bf16(o0[0], o0[1]); wo.y = cvt_pk_bf16(o0[2], o0[3]); wo.z = cvt_pk_bf16(o1[0], o1[1]); wo.w = cvt_pk_bf16(o1[2], o1[3]);
;                     *(u32x4*)(hp + off + bj * 128) = wo; } }
	s_nop 0
	v_lshlrev_b32_e32 v44, 16, v248
	v_and_b32_e32 v45, 0xffff0000, v248
	v_lshlrev_b32_e32 v46, 16, v249
	v_and_b32_e32 v47, 0xffff0000, v249
	v_lshlrev_b32_e32 v48, 16, v250
	v_and_b32_e32 v49, 0xffff0000, v250
	v_lshlrev_b32_e32 v50, 16, v251
	v_and_b32_e32 v51, 0xffff0000, v251
	v_pk_fma_f32 v[46:47], v[54:55], v[142:143], v[46:47]
	v_pk_fma_f32 v[44:45], v[52:53], v[140:141], v[44:45]
	v_pk_fma_f32 v[50:51], v[42:43], v[134:135], v[50:51]
	v_pk_fma_f32 v[42:43], v[40:41], v[132:133], v[48:49]
	v_cvt_pk_bf16_f32 v40, v44, v45
	v_cvt_pk_bf16_f32 v41, v46, v47
	v_lshl_add_u64 v[48:49], v[176:177], 0, v[164:165]
	v_cvt_pk_bf16_f32 v42, v42, v43
	v_cvt_pk_bf16_f32 v43, v50, v51
	s_nop 0
	global_store_dwordx4 v[64:65], v[40:43], off
	s_waitcnt vmcnt(14)
	s_nop 0
	v_lshlrev_b32_e32 v40, 16, v212
	v_and_b32_e32 v41, 0xffff0000, v212
	v_lshlrev_b32_e32 v42, 16, v213
	v_and_b32_e32 v43, 0xffff0000, v213
	v_lshlrev_b32_e32 v44, 16, v214
	v_and_b32_e32 v45, 0xffff0000, v214
	v_lshlrev_b32_e32 v46, 16, v215
	v_and_b32_e32 v47, 0xffff0000, v215
	v_pk_fma_f32 v[34:35], v[34:35], v[126:127], v[42:43]
	v_pk_fma_f32 v[32:33], v[32:33], v[124:125], v[40:41]
	v_pk_fma_f32 v[40:41], v[30:31], v[122:123], v[46:47]
	v_pk_fma_f32 v[30:31], v[28:29], v[120:121], v[44:45]
	v_cvt_pk_bf16_f32 v28, v32, v33
	v_cvt_pk_bf16_f32 v29, v34, v35
	s_nop 0
	v_cvt_pk_bf16_f32 v30, v30, v31
	v_cvt_pk_bf16_f32 v31, v40, v41
	s_nop 0
	global_store_dwordx4 v[64:65], v[28:31], off offset:256
	s_waitcnt vmcnt(13)
	s_nop 0
	v_lshlrev_b32_e32 v28, 16, v216
	v_and_b32_e32 v29, 0xffff0000, v216
	v_lshlrev_b32_e32 v30, 16, v217
	v_and_b32_e32 v31, 0xffff0000, v217
	v_lshlrev_b32_e32 v32, 16, v218
	v_and_b32_e32 v33, 0xffff0000, v218
	v_lshlrev_b32_e32 v34, 16, v219
	v_and_b32_e32 v35, 0xffff0000, v219
	v_pk_fma_f32 v[30:31], v[38:39], v[142:143], v[30:31]
	v_pk_fma_f32 v[28:29], v[36:37], v[140:141], v[28:29]
	v_pk_fma_f32 v[34:35], v[26:27], v[134:135], v[34:35]
	v_pk_fma_f32 v[26:27], v[24:25], v[132:133], v[32:33]
	v_cvt_pk_bf16_f32 v24, v28, v29
	v_cvt_pk_bf16_f32 v25, v30, v31
	v_lshl_add_u64 v[32:33], v[176:177], 0, v[166:167]
	v_cvt_pk_bf16_f32 v26, v26, v27
	v_cvt_pk_bf16_f32 v27, v34, v35
	s_nop 0
	global_store_dwordx4 v[48:49], v[24:27], off
	s_waitcnt vmcnt(12)
	s_nop 0
	v_lshlrev_b32_e32 v24, 16, v220
	v_and_b32_e32 v25, 0xffff0000, v220
	v_lshlrev_b32_e32 v26, 16, v221
	v_and_b32_e32 v27, 0xffff0000, v221
	v_lshlrev_b32_e32 v28, 16, v222
	v_and_b32_e32 v29, 0xffff0000, v222
	v_lshlrev_b32_e32 v30, 16, v223
	v_and_b32_e32 v31, 0xffff0000, v223
	v_pk_fma_f32 v[18:19], v[18:19], v[126:127], v[26:27]
	v_pk_fma_f32 v[16:17], v[16:17], v[124:125], v[24:25]
	v_pk_fma_f32 v[24:25], v[14:15], v[122:123], v[30:31]
	v_pk_fma_f32 v[14:15], v[12:13], v[120:121], v[28:29]
	v_cvt_pk_bf16_f32 v12, v16, v17
	v_cvt_pk_bf16_f32 v13, v18, v19
	s_nop 0
	v_cvt_pk_bf16_f32 v14, v14, v15
	v_cvt_pk_bf16_f32 v15, v24, v25
	s_nop 0
	global_store_dwordx4 v[48:49], v[12:15], off offset:256
	s_waitcnt vmcnt(11)
	s_nop 0
	v_lshlrev_b32_e32 v12, 16, v224
	v_and_b32_e32 v13, 0xffff0000, v224
	v_lshlrev_b32_e32 v14, 16, v225
	v_and_b32_e32 v15, 0xffff0000, v225
	v_lshlrev_b32_e32 v16, 16, v226
	v_and_b32_e32 v17, 0xffff0000, v226
	v_lshlrev_b32_e32 v18, 16, v227
	v_and_b32_e32 v19, 0xffff0000, v227
	v_pk_fma_f32 v[14:15], v[22:23], v[142:143], v[14:15]
	v_pk_fma_f32 v[12:13], v[20:21], v[140:141], v[12:13]
	v_pk_fma_f32 v[18:19], v[10:11], v[134:135], v[18:19]
	v_pk_fma_f32 v[10:11], v[8:9], v[132:133], v[16:17]
	v_cvt_pk_bf16_f32 v8, v12, v13
	v_cvt_pk_bf16_f32 v9, v14, v15
	s_nop 0
	v_cvt_pk_bf16_f32 v10, v10, v11
	v_cvt_pk_bf16_f32 v11, v18, v19
	s_nop 0
	global_store_dwordx4 v[32:33], v[8:11], off
	s_waitcnt vmcnt(10)
	s_nop 0
	v_lshlrev_b32_e32 v8, 16, v228
	v_and_b32_e32 v9, 0xffff0000, v228
	v_lshlrev_b32_e32 v10, 16, v229
	v_and_b32_e32 v11, 0xffff0000, v229
	v_lshlrev_b32_e32 v12, 16, v230
	v_and_b32_e32 v13, 0xffff0000, v230
	v_lshlrev_b32_e32 v14, 16, v231
	v_and_b32_e32 v15, 0xffff0000, v231
	v_pk_fma_f32 v[4:5], v[4:5], v[124:125], v[8:9]
	v_pk_fma_f32 v[8:9], v[2:3], v[122:123], v[14:15]
	v_pk_fma_f32 v[2:3], v[0:1], v[120:121], v[12:13]
	v_pk_fma_f32 v[6:7], v[6:7], v[126:127], v[10:11]
	v_cvt_pk_bf16_f32 v0, v4, v5
	s_nop 0
	v_cvt_pk_bf16_f32 v1, v6, v7
	v_cvt_pk_bf16_f32 v2, v2, v3
	v_cvt_pk_bf16_f32 v3, v8, v9
	global_store_dwordx4 v[32:33], v[0:3], off offset:256
	s_cbranch_vccnz .LBB0_918
	s_andn2_b64 vcc, exec, s[2:3]
	s_cbranch_vccnz .LBB0_917
	s_barrier
	s_branch .LBB0_917

; __device__ __forceinline__ unsigned cvt_pk_bf16(float lo, float hi) { unsigned r; asm volatile("v_cvt_pk_bf16_f32 %0, %1, %2" : "=v"(r) : "v"(lo), "v"(hi)); return r; }
; __device__ __forceinline__ float bflo(unsigned w) { return __uint_as_float(w << 16); }
; __device__ __forceinline__ float bfhi(unsigned w) { return __uint_as_float(w & 0xffff0000u); }
;     __device__ __forceinline__ void operator()(const f32x4 (&acc)[2][2][4][2], const Unit& u, int wr, int wc, int fr, int fq) const {
;         const int grow = rowoff + u.pm * 256; const bool lat = grow < MLAT; const int cond = lat ? (grow >> 13) : 8;
;         const float* bf = lat ? base_l + (size_t)grow * DM : base_c + (size_t)(grow - MLAT) * DM;
;         bf16_t* hp = hb + (size_t)grow * DM;
;         const int col0 = u.pn * 256 + wc * 32 + 8 * fq; const float* g = gate + cond * 6144 + col0;
;         f32x4 gv[2][2];
; #pragma unroll
;         for (int bj = 0; bj < 2; ++bj)
; #pragma unroll
;             for (int n = 0; n < 2; ++n) gv[bj][n] = *(const f32x4*)(g + bj * 128 + n * 4);
; #pragma unroll
;         for (int ai = 0; ai < 2; ++ai)
; #pragma unroll
;             for (int m = 0; m < 4; ++m) { const size_t off = (size_t)(wr * 64 + fr + ai * 128 + m * 16) * DM + col0;
; #pragma unroll
;                 for (int bj = 0; bj < 2; ++bj) { f32x4 b0, b1;
;                     if (BASE_F32) { b0 = *(const f32x4*)(bf + off + bj * 128); b1 = *(const f32x4*)(bf + off + bj * 128 + 4); }
;                     else { const u32x4 w = *(const u32x4*)(hp + off + bj * 128); b0 = (f32x4){bflo(w.x), bfhi(w.x), bflo(w.y), bfhi(w.y)}; b1 = (f32x4){bflo(w.z), bfhi(w.z), bflo(w.w), bfhi(w.w)}; }
;                     const f32x4 o0 = b0 + gv[bj][0] * acc[ai][bj][m][0], o1 = b1 + gv[bj][1] * acc[ai][bj][m][1]; u32x4 wo;
;                     wo.x = cvt_pk_bf16(o0[0], o0[1]); wo.y = cvt_pk_bf16(o0[2], o0[3]); wo.z = cvt_pk_bf16(o1[0], o1[1]); wo.w = cvt_pk_bf16(o1[2], o1[3]);
;                     *(u32x4*)(hp + off + bj * 128) = wo; } }
.LBB0_1178:
	s_lshl_b32 s30, s83, 8
	s_add_i32 s30, s30, s43
	s_min_i32 s31, s30, 0x10000
	s_ashr_i32 s36, s31, 13
	s_mulk_i32 s36, 0x1800
	s_ashr_i32 s31, s30, 31
	s_ashr_i32 s37, s36, 31
	s_lshl_b64 s[30:31], s[30:31], 11
	s_lshl_b64 s[36:37], s[36:37], 2
	s_add_u32 s36, s71, s36
	s_addc_u32 s37, s58, s37
	v_lshl_or_b32 v122, s82, 8, v183
	s_add_u32 s30, s68, s30
	v_ashrrev_i32_e32 v123, 31, v122
	s_addc_u32 s31, s69, s31
	v_lshl_add_u64 v[180:181], v[122:123], 1, s[30:31]
	v_lshl_add_u64 v[190:191], v[180:181], 0, v[160:161]
	global_load_dwordx4 v[186:189], v[190:191], off
	v_lshl_add_u64 v[126:127], v[122:123], 2, s[36:37]
	global_load_dwordx4 v[142:145], v[126:127], off
	global_load_dwordx4 v[134:137], v[126:127], off offset:16
	global_load_dwordx4 v[122:125], v[126:127], off offset:528
	s_nop 0
	global_load_dwordx4 v[126:129], v[126:127], off offset:512
	s_and_b64 vcc, exec, s[38:39]
	s_mov_b64 s[30:31], -1
	v_lshl_add_u64 v[252:253], v[180:181], 0, v[160:161]
	global_load_dwordx4 v[212:215], v[252:253], off offset:256
	v_lshl_add_u64 v[252:253], v[180:181], 0, v[162:163]
	global_load_dwordx4 v[216:219], v[252:253], off
	v_lshl_add_u64 v[252:253], v[180:181], 0, v[162:163]
	global_load_dwordx4 v[220:223], v[252:253], off offset:256
	v_lshl_add_u64 v[252:253], v[180:181], 0, v[164:165]
	global_load_dwordx4 v[224:227], v[252:253], off
	v_lshl_add_u64 v[252:253], v[180:181], 0, v[164:165]
	global_load_dwordx4 v[228:231], v[252:253], off offset:256
	v_lshl_add_u64 v[252:253], v[180:181], 0, v[166:167]
	global_load_dwordx4 v[232:235], v[252:253], off
	v_lshl_add_u64 v[252:253], v[180:181], 0, v[166:167]
	global_load_dwordx4 v[236:239], v[252:253], off offset:256
	v_lshl_add_u64 v[252:253], v[180:181], 0, v[168:169]
	global_load_dwordx4 v[240:243], v[252:253], off
	v_lshl_add_u64 v[252:253], v[180:181], 0, v[168:169]
	global_load_dwordx4 v[244:247], v[252:253], off offset:256
	v_lshl_add_u64 v[252:253], v[180:181], 0, v[170:171]
	global_load_dwordx4 v[248:251], v[252:253], off
	s_waitcnt vmcnt(10)
	v_lshlrev_b32_e32 v196, 16, v186
	v_and_b32_e32 v197, 0xffff0000, v186
	v_lshlrev_b32_e32 v186, 16, v187
	v_and_b32_e32 v187, 0xffff0000, v187
	v_lshlrev_b32_e32 v198, 16, v188
	v_and_b32_e32 v199, 0xffff0000, v188
	v_lshlrev_b32_e32 v188, 16, v189
	v_and_b32_e32 v189, 0xffff0000, v189
	v_pk_fma_f32 v[140:141], v[140:141], v[144:145], v[186:187]
	v_pk_fma_f32 v[138:139], v[138:139], v[142:143], v[196:197]
	v_pk_fma_f32 v[186:187], v[132:133], v[136:137], v[188:189]
	v_pk_fma_f32 v[132:133], v[130:131], v[134:135], v[198:199]
	v_cvt_pk_bf16_f32 v130, v138, v139
	v_cvt_pk_bf16_f32 v131, v140, v141
	s_nop 0
	v_cvt_pk_bf16_f32 v132, v132, v133
	v_cvt_pk_bf16_f32 v133, v186, v187
	v_lshl_add_u64 v[186:187], v[180:181], 0, v[162:163]
	global_store_dwordx4 v[190:191], v[130:133], off
	s_waitcnt vmcnt(10)
	s_nop 0
	v_lshlrev_b32_e32 v130, 16, v212
	v_and_b32_e32 v131, 0xffff0000, v212
	v_lshlrev_b32_e32 v132, 16, v213
	v_and_b32_e32 v133, 0xffff0000, v213
	v_lshlrev_b32_e32 v138, 16, v214
	v_and_b32_e32 v139, 0xffff0000, v214
	v_lshlrev_b32_e32 v140, 16, v215
	v_and_b32_e32 v141, 0xffff0000, v215
	v_pk_fma_f32 v[116:117], v[116:117], v[128:129], v[132:133]
	v_pk_fma_f32 v[114:115], v[114:115], v[126:127], v[130:131]
	v_pk_fma_f32 v[130:131], v[112:113], v[124:125], v[140:141]
	v_pk_fma_f32 v[112:113], v[110:111], v[122:123], v[138:139]
	v_cvt_pk_bf16_f32 v110, v114, v115
	v_cvt_pk_bf16_f32 v111, v116, v117
	s_nop 0
	v_cvt_pk_bf16_f32 v112, v112, v113
	v_cvt_pk_bf16_f32 v113, v130, v131
	v_lshl_add_u64 v[252:253], v[180:181], 0, v[170:171]
	global_load_dwordx4 v[212:215], v[252:253], off offset:256
	s_nop 0
	global_store_dwordx4 v[190:191], v[110:113], off offset:256
	s_waitcnt vmcnt(11)
	s_nop 0
	v_lshlrev_b32_e32 v110, 16, v216
	v_and_b32_e32 v111, 0xffff0000, v216
	v_lshlrev_b32_e32 v112, 16, v217
	v_and_b32_e32 v113, 0xffff0000, v217
	v_lshlrev_b32_e32 v114, 16, v218
	v_and_b32_e32 v115, 0xffff0000, v218
	v_lshlrev_b32_e32 v116, 16, v219
	v_and_b32_e32 v117, 0xffff0000, v219
	v_pk_fma_f32 v[112:113], v[120:121], v[144:145], v[112:113]
	v_pk_fma_f32 v[110:111], v[118:119], v[142:143], v[110:111]
	v_pk_fma_f32 v[116:117], v[108:109], v[136:137], v[116:117]
	v_pk_fma_f32 v[108:109], v[106:107], v[134:135], v[114:115]
	v_cvt_pk_bf16_f32 v106, v110, v111
	v_cvt_pk_bf16_f32 v107, v112, v113
	v_lshl_add_u64 v[114:115], v[180:181], 0, v[164:165]
	v_cvt_pk_bf16_f32 v108, v108, v109
	v_cvt_pk_bf16_f32 v109, v116, v117
	v_lshl_add_u64 v[252:253], v[180:181], 0, v[172:173]
	global_load_dwordx4 v[216:219], v[252:253], off
	s_nop 0
	global_store_dwordx4 v[186:187], v[106:109], off
	s_waitcnt vmcnt(12)
	s_nop 0
	v_lshlrev_b32_e32 v106, 16, v220
	v_and_b32_e32 v107, 0xffff0000, v220
	v_lshlrev_b32_e32 v108, 16, v221
	v_and_b32_e32 v109, 0xffff0000, v221
	v_lshlrev_b32_e32 v110, 16, v222
	v_and_b32_e32 v111, 0xffff0000, v222
	v_lshlrev_b32_e32 v112, 16, v223
	v_and_b32_e32 v113, 0xffff0000, v223
	v_pk_fma_f32 v[100:101], v[100:101], v[128:129], v[108:109]
	v_pk_fma_f32 v[98:99], v[98:99], v[126:127], v[106:107]
	v_pk_fma_f32 v[106:107], v[96:97], v[124:125], v[112:113]
	v_pk_fma_f32 v[96:97], v[94:95], v[122:123], v[110:111]
	v_cvt_pk_bf16_f32 v94, v98, v99
	v_cvt_pk_bf16_f32 v95, v100, v101
	s_nop 0
	v_cvt_pk_bf16_f32 v96, v96, v97
	v_cvt_pk_bf16_f32 v97, v106, v107
	v_lshl_add_u64 v[252:253], v[180:181], 0, v[172:173]
	global_load_dwordx4 v[220:223], v[252:253], off offset:256
	s_nop 0
	global_store_dwordx4 v[186:187], v[94:97], off offset:256
	s_waitcnt vmcnt(13)
; __device__ __forceinline__ unsigned cvt_pk_bf16(float lo, float hi) { unsigned r; asm volatile("v_cvt_pk_bf16_f32 %0, %1, %2" : "=v"(r) : "v"(lo), "v"(hi)); return r; }
; __device__ __forceinline__ float bflo(unsigned w) { return __uint_as_float(w << 16); }
; __device__ __forceinline__ float bfhi(unsigned w) { return __uint_as_float(w & 0xffff0000u); }
;     __device__ __forceinline__ void operator()(const f32x4 (&acc)[2][2][4][2], const Unit& u, int wr, int wc, int fr, int fq) const {
;     ...
;         for (int ai = 0; ai < 2; ++ai)
; #pragma unroll
;             for (int m = 0; m < 4; ++m) { const size_t off = (size_t)(wr * 64 + fr + ai * 128 + m * 16) * DM + col0;
; #pragma unroll
;                 for (int bj = 0; bj < 2; ++bj) { f32x4 b0, b1;
;                     if (BASE_F32) { b0 = *(const f32x4*)(bf + off + bj * 128); b1 = *(const f32x4*)(bf + off + bj * 128 + 4); }
;                     else { const u32x4 w = *(const u32x4*)(hp + off + bj * 128); b0 = (f32x4){bflo(w.x), bfhi(w.x), bflo(w.y), bfhi(w.y)}; b1 = (f32x4){bflo(w.z), bfhi(w.z), bflo(w.w), bfhi(w.w)}; }
;                     const f32x4 o0 = b0 + gv[bj][0] * acc[ai][bj][m][0], o1 = b1 + gv[bj][1] * acc[ai][bj][m][1]; u32x4 wo;
;                     wo.x = cvt_pk_bf16(o0[0], o0[1]); wo.y = cvt_pk_bf16(o0[2], o0[3]); wo.z = cvt_pk_bf16(o1[0], o1[1]); wo.w = cvt_pk_bf16(o1[2], o1[3]);
;                     *(u32x4*)(hp + off + bj * 128) = wo; } }
	s_nop 0
	v_lshlrev_b32_e32 v94, 16, v224
	v_and_b32_e32 v95, 0xffff0000, v224
	v_lshlrev_b32_e32 v96, 16, v225
	v_and_b32_e32 v97, 0xffff0000, v225
	v_lshlrev_b32_e32 v98, 16, v226
	v_and_b32_e32 v99, 0xffff0000, v226
	v_lshlrev_b32_e32 v100, 16, v227
	v_and_b32_e32 v101, 0xffff0000, v227
	v_pk_fma_f32 v[96:97], v[104:105], v[144:145], v[96:97]
	v_pk_fma_f32 v[94:95], v[102:103], v[142:143], v[94:95]
	v_pk_fma_f32 v[100:101], v[92:93], v[136:137], v[100:101]
	v_pk_fma_f32 v[92:93], v[90:91], v[134:135], v[98:99]
	v_cvt_pk_bf16_f32 v90, v94, v95
	v_cvt_pk_bf16_f32 v91, v96, v97
	v_lshl_add_u64 v[98:99], v[180:181], 0, v[166:167]
	v_cvt_pk_bf16_f32 v92, v92, v93
	v_cvt_pk_bf16_f32 v93, v100, v101
	v_lshl_add_u64 v[252:253], v[180:181], 0, v[174:175]
	global_load_dwordx4 v[224:227], v[252:253], off
	s_nop 0
	global_store_dwordx4 v[114:115], v[90:93], off
	s_waitcnt vmcnt(14)
	s_nop 0
	v_lshlrev_b32_e32 v90, 16, v228
	v_and_b32_e32 v91, 0xffff0000, v228
	v_lshlrev_b32_e32 v92, 16, v229
	v_and_b32_e32 v93, 0xffff0000, v229
	v_lshlrev_b32_e32 v94, 16, v230
	v_and_b32_e32 v95, 0xffff0000, v230
	v_lshlrev_b32_e32 v96, 16, v231
	v_and_b32_e32 v97, 0xffff0000, v231
	v_pk_fma_f32 v[84:85], v[84:85], v[128:129], v[92:93]
	v_pk_fma_f32 v[82:83], v[82:83], v[126:127], v[90:91]
	v_pk_fma_f32 v[90:91], v[80:81], v[124:125], v[96:97]
	v_pk_fma_f32 v[80:81], v[78:79], v[122:123], v[94:95]
	v_cvt_pk_bf16_f32 v78, v82, v83
	v_cvt_pk_bf16_f32 v79, v84, v85
	s_nop 0
	v_cvt_pk_bf16_f32 v80, v80, v81
	v_cvt_pk_bf16_f32 v81, v90, v91
	v_lshl_add_u64 v[252:253], v[180:181], 0, v[174:175]
	global_load_dwordx4 v[228:231], v[252:253], off offset:256
	s_nop 0
	global_store_dwordx4 v[114:115], v[78:81], off offset:256
	s_waitcnt vmcnt(15)
	s_nop 0
	v_lshlrev_b32_e32 v78, 16, v232
	v_and_b32_e32 v79, 0xffff0000, v232
	v_lshlrev_b32_e32 v80, 16, v233
	v_and_b32_e32 v81, 0xffff0000, v233
	v_lshlrev_b32_e32 v82, 16, v234
	v_and_b32_e32 v83, 0xffff0000, v234
	v_lshlrev_b32_e32 v84, 16, v235
	v_and_b32_e32 v85, 0xffff0000, v235
	v_pk_fma_f32 v[80:81], v[88:89], v[144:145], v[80:81]
	v_pk_fma_f32 v[78:79], v[86:87], v[142:143], v[78:79]
	v_pk_fma_f32 v[84:85], v[76:77], v[136:137], v[84:85]
	v_pk_fma_f32 v[76:77], v[74:75], v[134:135], v[82:83]
	v_cvt_pk_bf16_f32 v74, v78, v79
	v_cvt_pk_bf16_f32 v75, v80, v81
	v_lshl_add_u64 v[82:83], v[180:181], 0, v[168:169]
	v_cvt_pk_bf16_f32 v76, v76, v77
	v_cvt_pk_bf16_f32 v77, v84, v85
	s_nop 0
	global_store_dwordx4 v[98:99], v[74:77], off
	s_waitcnt vmcnt(15)
	s_nop 0
	v_lshlrev_b32_e32 v74, 16, v236
	v_and_b32_e32 v75, 0xffff0000, v236
	v_lshlrev_b32_e32 v76, 16, v237
	v_and_b32_e32 v77, 0xffff0000, v237
	v_lshlrev_b32_e32 v78, 16, v238
	v_and_b32_e32 v79, 0xffff0000, v238
	v_lshlrev_b32_e32 v80, 16, v239
	v_and_b32_e32 v81, 0xffff0000, v239
	v_pk_fma_f32 v[72:73], v[72:73], v[128:129], v[76:77]
	v_pk_fma_f32 v[70:71], v[70:71], v[126:127], v[74:75]
	v_pk_fma_f32 v[74:75], v[68:69], v[124:125], v[80:81]
	v_pk_fma_f32 v[68:69], v[66:67], v[122:123], v[78:79]
	v_cvt_pk_bf16_f32 v66, v70, v71
	v_cvt_pk_bf16_f32 v67, v72, v73
	s_nop 0
	v_cvt_pk_bf16_f32 v68, v68, v69
	v_cvt_pk_bf16_f32 v69, v74, v75
	s_nop 0
	global_store_dwordx4 v[98:99], v[66:69], off offset:256
	s_waitcnt vmcnt(15)
	s_nop 0
	v_lshlrev_b32_e32 v66, 16, v240
	v_and_b32_e32 v67, 0xffff0000, v240
	v_lshlrev_b32_e32 v68, 16, v241
	v_and_b32_e32 v69, 0xffff0000, v241
	v_lshlrev_b32_e32 v70, 16, v242
	v_and_b32_e32 v71, 0xffff0000, v242
	v_lshlrev_b32_e32 v72, 16, v243
	v_and_b32_e32 v73, 0xffff0000, v243
	v_pk_fma_f32 v[64:65], v[64:65], v[144:145], v[68:69]
	v_pk_fma_f32 v[62:63], v[62:63], v[142:143], v[66:67]
	v_pk_fma_f32 v[66:67], v[60:61], v[136:137], v[72:73]
	v_pk_fma_f32 v[60:61], v[58:59], v[134:135], v[70:71]
	v_cvt_pk_bf16_f32 v58, v62, v63
	v_cvt_pk_bf16_f32 v59, v64, v65
	s_nop 0
	v_cvt_pk_bf16_f32 v60, v60, v61
	v_cvt_pk_bf16_f32 v61, v66, v67
	v_lshl_add_u64 v[66:67], v[180:181], 0, v[170:171]
	global_store_dwordx4 v[82:83], v[58:61], off
	s_waitcnt vmcnt(15)
	s_nop 0
	v_lshlrev_b32_e32 v58, 16, v244
	v_and_b32_e32 v59, 0xffff0000, v244
	v_lshlrev_b32_e32 v60, 16, v245
	v_and_b32_e32 v61, 0xffff0000, v245
	v_lshlrev_b32_e32 v62, 16, v246
	v_and_b32_e32 v63, 0xffff0000, v246
	v_lshlrev_b32_e32 v64, 16, v247
	v_and_b32_e32 v65, 0xffff0000, v247
	v_pk_fma_f32 v[52:53], v[52:53], v[128:129], v[60:61]
	v_pk_fma_f32 v[50:51], v[50:51], v[126:127], v[58:59]
	v_pk_fma_f32 v[58:59], v[48:49], v[124:125], v[64:65]
	v_pk_fma_f32 v[48:49], v[46:47], v[122:123], v[62:63]
	v_cvt_pk_bf16_f32 v46, v50, v51
	v_cvt_pk_bf16_f32 v47, v52, v53
	s_nop 0
	v_cvt_pk_bf16_f32 v48, v48, v49
	v_cvt_pk_bf16_f32 v49, v58, v59
	s_nop 0
	global_store_dwordx4 v[82:83], v[46:49], off offset:256
	s_waitcnt vmcnt(15)
; __device__ __forceinline__ unsigned cvt_pk_bf16(float lo, float hi) { unsigned r; asm volatile("v_cvt_pk_bf16_f32 %0, %1, %2" : "=v"(r) : "v"(lo), "v"(hi)); return r; }
; __device__ __forceinline__ float bflo(unsigned w) { return __uint_as_float(w << 16); }
; __device__ __forceinline__ float bfhi(unsigned w) { return __uint_as_float(w & 0xffff0000u); }
;     __device__ __forceinline__ void operator()(const f32x4 (&acc)[2][2][4][2], const Unit& u, int wr, int wc, int fr, int fq) const {
;     ...
;             for (int m = 0; m < 4; ++m) { const size_t off = (size_t)(wr * 64 + fr + ai * 128 + m * 16) * DM + col0;
; #pragma unroll
;                 for (int bj = 0; bj < 2; ++bj) { f32x4 b0, b1;
;                     if (BASE_F32) { b0 = *(const f32x4*)(bf + off + bj * 128); b1 = *(const f32x4*)(bf + off + bj * 128 + 4); }
;                     else { const u32x4 w = *(const u32x4*)(hp + off + bj * 128); b0 = (f32x4){bflo(w.x), bfhi(w.x), bflo(w.y), bfhi(w.y)}; b1 = (f32x4){bflo(w.z), bfhi(w.z), bflo(w.w), bfhi(w.w)}; }
;                     const f32x4 o0 = b0 + gv[bj][0] * acc[ai][bj][m][0], o1 = b1 + gv[bj][1] * acc[ai][bj][m][1]; u32x4 wo;
;                     wo.x = cvt_pk_bf16(o0[0], o0[1]); wo.y = cvt_pk_bf16(o0[2], o0[3]); wo.z = cvt_pk_bf16(o1[0], o1[1]); wo.w = cvt_pk_bf16(o1[2], o1[3]);
;                     *(u32x4*)(hp + off + bj * 128) = wo; } }
	s_nop 0
	v_lshlrev_b32_e32 v46, 16, v248
	v_and_b32_e32 v47, 0xffff0000, v248
	v_lshlrev_b32_e32 v48, 16, v249
	v_and_b32_e32 v49, 0xffff0000, v249
	v_lshlrev_b32_e32 v50, 16, v250
	v_and_b32_e32 v51, 0xffff0000, v250
	v_lshlrev_b32_e32 v52, 16, v251
	v_and_b32_e32 v53, 0xffff0000, v251
	v_pk_fma_f32 v[48:49], v[56:57], v[144:145], v[48:49]
	v_pk_fma_f32 v[46:47], v[54:55], v[142:143], v[46:47]
	v_pk_fma_f32 v[52:53], v[44:45], v[136:137], v[52:53]
	v_pk_fma_f32 v[44:45], v[42:43], v[134:135], v[50:51]
	v_cvt_pk_bf16_f32 v42, v46, v47
	v_cvt_pk_bf16_f32 v43, v48, v49
	v_lshl_add_u64 v[50:51], v[180:181], 0, v[172:173]
	v_cvt_pk_bf16_f32 v44, v44, v45
	v_cvt_pk_bf16_f32 v45, v52, v53
	s_nop 0
	global_store_dwordx4 v[66:67], v[42:45], off
	s_waitcnt vmcnt(14)
	s_nop 0
	v_lshlrev_b32_e32 v42, 16, v212
	v_and_b32_e32 v43, 0xffff0000, v212
	v_lshlrev_b32_e32 v44, 16, v213
	v_and_b32_e32 v45, 0xffff0000, v213
	v_lshlrev_b32_e32 v46, 16, v214
	v_and_b32_e32 v47, 0xffff0000, v214
	v_lshlrev_b32_e32 v48, 16, v215
	v_and_b32_e32 v49, 0xffff0000, v215
	v_pk_fma_f32 v[36:37], v[36:37], v[128:129], v[44:45]
	v_pk_fma_f32 v[34:35], v[34:35], v[126:127], v[42:43]
	v_pk_fma_f32 v[42:43], v[32:33], v[124:125], v[48:49]
	v_pk_fma_f32 v[32:33], v[30:31], v[122:123], v[46:47]
	v_cvt_pk_bf16_f32 v30, v34, v35
	v_cvt_pk_bf16_f32 v31, v36, v37
	s_nop 0
	v_cvt_pk_bf16_f32 v32, v32, v33
	v_cvt_pk_bf16_f32 v33, v42, v43
	s_nop 0
	global_store_dwordx4 v[66:67], v[30:33], off offset:256
	s_waitcnt vmcnt(13)
	s_nop 0
	v_lshlrev_b32_e32 v30, 16, v216
	v_and_b32_e32 v31, 0xffff0000, v216
	v_lshlrev_b32_e32 v32, 16, v217
	v_and_b32_e32 v33, 0xffff0000, v217
	v_lshlrev_b32_e32 v34, 16, v218
	v_and_b32_e32 v35, 0xffff0000, v218
	v_lshlrev_b32_e32 v36, 16, v219
	v_and_b32_e32 v37, 0xffff0000, v219
	v_pk_fma_f32 v[32:33], v[40:41], v[144:145], v[32:33]
	v_pk_fma_f32 v[30:31], v[38:39], v[142:143], v[30:31]
	v_pk_fma_f32 v[36:37], v[28:29], v[136:137], v[36:37]
	v_pk_fma_f32 v[28:29], v[26:27], v[134:135], v[34:35]
	v_cvt_pk_bf16_f32 v26, v30, v31
	v_cvt_pk_bf16_f32 v27, v32, v33
	v_lshl_add_u64 v[34:35], v[180:181], 0, v[174:175]
	v_cvt_pk_bf16_f32 v28, v28, v29
	v_cvt_pk_bf16_f32 v29, v36, v37
	s_nop 0
	global_store_dwordx4 v[50:51], v[26:29], off
	s_waitcnt vmcnt(12)
	s_nop 0
	v_lshlrev_b32_e32 v26, 16, v220
	v_and_b32_e32 v27, 0xffff0000, v220
	v_lshlrev_b32_e32 v28, 16, v221
	v_and_b32_e32 v29, 0xffff0000, v221
	v_lshlrev_b32_e32 v30, 16, v222
	v_and_b32_e32 v31, 0xffff0000, v222
	v_lshlrev_b32_e32 v32, 16, v223
	v_and_b32_e32 v33, 0xffff0000, v223
	v_pk_fma_f32 v[20:21], v[20:21], v[128:129], v[28:29]
	v_pk_fma_f32 v[18:19], v[18:19], v[126:127], v[26:27]
	v_pk_fma_f32 v[26:27], v[16:17], v[124:125], v[32:33]
	v_pk_fma_f32 v[16:17], v[14:15], v[122:123], v[30:31]
	v_cvt_pk_bf16_f32 v14, v18, v19
	v_cvt_pk_bf16_f32 v15, v20, v21
	s_nop 0
	v_cvt_pk_bf16_f32 v16, v16, v17
	v_cvt_pk_bf16_f32 v17, v26, v27
	s_nop 0
	global_store_dwordx4 v[50:51], v[14:17], off offset:256
	s_waitcnt vmcnt(11)
	s_nop 0
	v_lshlrev_b32_e32 v14, 16, v224
	v_and_b32_e32 v15, 0xffff0000, v224
	v_lshlrev_b32_e32 v16, 16, v225
	v_and_b32_e32 v17, 0xffff0000, v225
	v_lshlrev_b32_e32 v18, 16, v226
	v_and_b32_e32 v19, 0xffff0000, v226
	v_lshlrev_b32_e32 v20, 16, v227
	v_and_b32_e32 v21, 0xffff0000, v227
	v_pk_fma_f32 v[16:17], v[24:25], v[144:145], v[16:17]
	v_pk_fma_f32 v[14:15], v[22:23], v[142:143], v[14:15]
	v_pk_fma_f32 v[20:21], v[12:13], v[136:137], v[20:21]
	v_pk_fma_f32 v[12:13], v[10:11], v[134:135], v[18:19]
	v_cvt_pk_bf16_f32 v10, v14, v15
	v_cvt_pk_bf16_f32 v11, v16, v17
	s_nop 0
	v_cvt_pk_bf16_f32 v12, v12, v13
	v_cvt_pk_bf16_f32 v13, v20, v21
	s_nop 0
	global_store_dwordx4 v[34:35], v[10:13], off
	s_waitcnt vmcnt(10)
	s_nop 0
	v_lshlrev_b32_e32 v10, 16, v228
	v_and_b32_e32 v11, 0xffff0000, v228
	v_lshlrev_b32_e32 v12, 16, v229
	v_and_b32_e32 v13, 0xffff0000, v229
	v_lshlrev_b32_e32 v14, 16, v230
	v_and_b32_e32 v15, 0xffff0000, v230
	v_lshlrev_b32_e32 v16, 16, v231
	v_and_b32_e32 v17, 0xffff0000, v231
	v_pk_fma_f32 v[6:7], v[6:7], v[126:127], v[10:11]
	v_pk_fma_f32 v[10:11], v[4:5], v[124:125], v[16:17]
	v_pk_fma_f32 v[4:5], v[2:3], v[122:123], v[14:15]
	v_pk_fma_f32 v[8:9], v[8:9], v[128:129], v[12:13]
	v_cvt_pk_bf16_f32 v2, v6, v7
	s_nop 0
	v_cvt_pk_bf16_f32 v3, v8, v9
	v_cvt_pk_bf16_f32 v4, v4, v5
	v_cvt_pk_bf16_f32 v5, v10, v11
	global_store_dwordx4 v[34:35], v[2:5], off offset:256
	s_cbranch_vccnz .LBB0_1163
	s_andn2_b64 vcc, exec, s[34:35]
	s_cbranch_vccnz .LBB0_1162
	s_barrier
	s_branch .LBB0_1162
